# MoBA unit prologue: first two K/V tile loads issued before the block selection instead of after it
# speedup vs baseline: 1.0103x; 1.0033x over previous
; #define LAS __attribute__((address_space(3)))
; DI int tid_opaque() { int t = threadIdx.x; asm volatile("" : "+v"(t)); return t; }
; DI float bf_lo(unsigned u) { return __uint_as_float(u << 16); }
; template <int MODE>
; DI void attn_unit(unsigned char* ws, int b, int h, int qb, LAS unsigned char* lds, bool do_store = true) {
;     ...
;     const int tid = tid_opaque(), lane = tid & 63, w = __builtin_amdgcn_readfirstlane(tid >> 6), r = lane & 31, hh = lane >> 5;
;     const int q0 = qb * 256; const long rowbase = (long)b * SEQ;
;     const int qg = q0 + 32 * w + r;
;     bf16x8 qf[NS];
;     { const bf16_t* qrow = Qb + (size_t)(rowbase + qg) * QPITCH + qcol + 8 * hh;
; #pragma unroll
;       for (int s = 0; s < NS; ++s) qf[s] = *(const bf16x8*)(qrow + 16 * s); }
;     unsigned mysel = 0;
;     if (MODE == 2) {
;         if (tid < 256) {
;             const bf16_t* qr = Qb + (size_t)(rowbase + q0 + tid) * QPITCH + qcol;
;             float qv[64];
; #pragma unroll
;             for (int c8 = 0; c8 < 8; ++c8) { const u32x4 u = *(const u32x4*)(qr + c8 * 8);
; #pragma unroll
;                 for (int e = 0; e < 4; ++e) { qv[c8 * 8 + 2 * e] = bf_lo(u[e]); qv[c8 * 8 + 2 * e + 1] = bf_hi(u[e]); } }
;             const float* km = (const float*)(ws + WS_KMEAN) + (size_t)((b * 8 + h) * 16) * 64;
;             float v0 = -INFINITY, v1 = -INFINITY, v2 = -INFINITY; int i0 = -1, i1 = -1, i2 = -1;
;             for (int n = 0; n < qb; ++n) { float d = 0.f;
; #pragma unroll
;                 for (int e = 0; e < 64; ++e) d += qv[e] * km[n * 64 + e];
;                 if (d > v0) { v2 = v1; i2 = i1; v1 = v0; i1 = i0; v0 = d; i0 = n; }
;                 else if (d > v1) { v2 = v1; i2 = i1; v1 = d; i1 = n; }
;                 else if (d > v2) { v2 = d; i2 = n; } }
;             unsigned mk = 0; if (i0 >= 0) mk |= 1u << i0; if (i1 >= 0) mk |= 1u << i1; if (i2 >= 0) mk |= 1u << i2;
;             *(LAS unsigned*)(lds + AT_SEL + tid * 4) = mk;
;         }
;         __syncthreads();
;         mysel = *(LAS unsigned*)(lds + AT_SEL + (32 * w + r) * 4);
;     }
;     const int kkey = tid >> 3, kch = tid & 7, pkey = (tid & 255) >> 2, pch = tid & 3;
;     u32x4 kr[2], vr[2], pr[2];
;     pr[0] = (u32x4){0u, 0u, 0u, 0u}; pr[1] = pr[0];
;     ...
;     const int kt_hi = qb * 4 + 3;
;     AT_LOADG(kt_hi, 0); AT_LOADG(kt_hi - 1, 1); AT_STORE(0, 0);
.LBB0_124:
	s_and_b64 vcc, exec, s[38:39]
	s_cbranch_vccz .LBB0_95
	s_ashr_i32 s46, s14, 7
	s_sub_i32 s30, 15, s46
	s_and_b32 s31, s14, 63
	s_and_b32 s2, s14, 64
	s_lshl_b32 s15, s30, 8
	s_cmp_lg_u32 s2, 0
	s_mov_b64 s[38:39], -1
	s_cbranch_scc0 .LBB0_174
	v_mov_b32_e32 v14, v210
	s_lshr_b32 s44, s31, 3
	v_readfirstlane_b32 s38, v14
	s_ashr_i32 s53, s38, 1
	s_andn2_b32 s53, s53, 31
	v_and_b32_e32 v28, 31, v14
	s_add_i32 s52, s53, s15
	s_waitcnt vmcnt(0)
	v_or_b32_e32 v158, s52, v28
	s_lshl_b32 s2, s44, 12
	v_ashrrev_i32_e32 v159, 31, v158
	v_lshl_add_u64 v[2:3], v[158:159], 0, s[2:3]
	v_mov_b64_e32 v[4:5], s[20:21]
	s_and_b32 s45, s14, 7
	v_mad_u64_u32 v[4:5], s[38:39], v2, s88, v[4:5]
	v_bfe_u32 v29, v14, 5, 1
	v_mad_i32_i24 v5, v3, s88, v5
	s_lshl_b32 s38, s45, 7
	s_mov_b32 s39, s3
	v_lshl_add_u64 v[156:157], v[4:5], 0, s[38:39]
	v_lshlrev_b32_e32 v0, 4, v29
	v_lshl_add_u64 v[2:3], v[156:157], 0, v[0:1]
	global_load_dwordx4 v[82:85], v[2:3], off
	global_load_dwordx4 v[86:89], v[2:3], off offset:32
	global_load_dwordx4 v[90:93], v[2:3], off offset:64
	global_load_dwordx4 v[94:97], v[2:3], off offset:96
	s_lshl_b32 s48, s30, 2
	s_or_b32 s48, s48, 3
	s_lshl_b32 s48, s48, 6
	s_add_i32 s48, s48, s2
	s_mov_b32 s49, s3
	v_ashrrev_i32_e32 v140, 3, v14
	v_ashrrev_i32_e32 v141, 31, v140
	v_lshl_add_u64 v[142:143], v[140:141], 0, s[48:49]
	v_mov_b64_e32 v[144:145], s[20:21]
	v_mad_u64_u32 v[146:147], s[50:51], v142, s88, v[144:145]
	v_mad_i32_i24 v147, v143, s88, v147
	s_lshl_b32 s48, s45, 7
	s_mov_b32 s49, s3
	v_lshlrev_b32_e32 v148, 4, v14
	v_and_b32_e32 v148, 0x70, v148
	v_mov_b32_e32 v149, v1
	v_lshl_add_u64 v[142:143], v[146:147], 0, s[48:49]
	v_lshl_add_u64 v[142:143], v[142:143], 0, v[148:149]
	global_load_dwordx4 v[124:127], v[142:143], off offset:1024
	global_load_dwordx4 v[128:131], v[142:143], off offset:2048
	s_or_b32 s54, s15, 0x80
	s_mov_b32 s55, s3
	v_lshl_add_u64 v[150:151], v[140:141], 0, s[2:3]
	v_lshl_add_u64 v[142:143], v[150:151], 0, s[54:55]
	v_mad_u64_u32 v[146:147], s[50:51], v142, s88, v[144:145]
	v_mad_i32_i24 v147, v143, s88, v147
	v_lshl_add_u64 v[142:143], v[146:147], 0, s[48:49]
	v_lshl_add_u64 v[142:143], v[142:143], 0, v[148:149]
	global_load_dwordx4 v[132:135], v[142:143], off offset:1024
	global_load_dwordx4 v[136:139], v[142:143], off offset:2048
	s_movk_i32 s38, 0xff
	v_cmp_lt_i32_e32 vcc, s38, v14
	v_lshlrev_b32_e32 v30, 2, v14
	s_and_saveexec_b64 s[38:39], vcc
	s_xor_b64 s[38:39], exec, s[38:39]
	v_lshlrev_b32_e32 v30, 2, v14
	s_or_saveexec_b64 s[38:39], s[38:39]
	s_lshl_b32 s54, s45, 6
	s_xor_b64 exec, exec, s[38:39]
	s_cbranch_execz .LBB0_140
	v_mov_b32_e32 v4, -1
	s_cmp_eq_u32 s46, 15
	v_mov_b32_e32 v3, -1
	v_mov_b32_e32 v98, -1
	s_cbranch_scc1 .LBB0_139
	s_add_i32 s46, s15, s2
	s_mov_b32 s47, s3
	v_ashrrev_i32_e32 v15, 31, v14
	v_lshl_add_u64 v[2:3], v[14:15], 0, s[46:47]
	v_mov_b64_e32 v[4:5], s[20:21]
	v_mad_u64_u32 v[4:5], s[46:47], v2, s88, v[4:5]
	v_mad_i32_i24 v5, v3, s88, v5
	s_lshl_b32 s46, s54, 1
	s_mov_b32 s47, s3
	v_lshl_add_u64 v[20:21], v[4:5], 0, s[46:47]
	global_load_dwordx4 v[2:5], v[20:21], off offset:48
	global_load_dwordx4 v[6:9], v[20:21], off offset:32
	global_load_dwordx4 v[10:13], v[20:21], off offset:16
	global_load_dwordx4 v[16:19], v[20:21], off
	global_load_dwordx4 v[180:183], v[20:21], off offset:112
	global_load_dwordx4 v[184:187], v[20:21], off offset:96
	global_load_dwordx4 v[188:191], v[20:21], off offset:80
	global_load_dwordx4 v[192:195], v[20:21], off offset:64
	s_lshl_b32 s45, s45, 12
	s_lshl_b32 s44, s44, 15
	s_or_b32 s44, s44, s45
	s_add_u32 s44, s9, s44
	s_addc_u32 s45, s13, 0
	s_mov_b32 s55, 0
	v_mov_b32_e32 v102, -1
	v_mov_b32_e32 v100, 0xff800000
	v_mov_b32_e32 v101, 0xff800000
	v_mov_b32_e32 v103, 0xff800000
	v_mov_b32_e32 v99, -1
	v_mov_b32_e32 v98, -1
	s_waitcnt vmcnt(7)
	v_lshlrev_b32_e32 v54, 16, v2
	s_waitcnt vmcnt(6)
	v_lshlrev_b32_e32 v46, 16, v6
	s_waitcnt vmcnt(5)
	v_lshlrev_b32_e32 v38, 16, v10
	s_waitcnt vmcnt(4)
	v_lshlrev_b32_e32 v15, 16, v16
	v_and_b32_e32 v31, 0xffff0000, v16
	v_lshlrev_b32_e32 v32, 16, v17
	v_and_b32_e32 v33, 0xffff0000, v17
	v_lshlrev_b32_e32 v34, 16, v18
	v_and_b32_e32 v35, 0xffff0000, v18
	v_lshlrev_b32_e32 v36, 16, v19
	v_and_b32_e32 v37, 0xffff0000, v19
	v_and_b32_e32 v39, 0xffff0000, v10
	v_lshlrev_b32_e32 v40, 16, v11
	v_and_b32_e32 v41, 0xffff0000, v11
	v_lshlrev_b32_e32 v42, 16, v12
	v_and_b32_e32 v43, 0xffff0000, v12
	v_lshlrev_b32_e32 v44, 16, v13
	v_and_b32_e32 v45, 0xffff0000, v13
	v_and_b32_e32 v47, 0xffff0000, v6
	v_lshlrev_b32_e32 v48, 16, v7
	v_and_b32_e32 v49, 0xffff0000, v7
	v_lshlrev_b32_e32 v50, 16, v8
	v_and_b32_e32 v51, 0xffff0000, v8
	v_lshlrev_b32_e32 v52, 16, v9
	v_and_b32_e32 v53, 0xffff0000, v9
	v_and_b32_e32 v55, 0xffff0000, v2
	v_lshlrev_b32_e32 v56, 16, v3
	v_and_b32_e32 v57, 0xffff0000, v3
	v_lshlrev_b32_e32 v58, 16, v4
	v_and_b32_e32 v59, 0xffff0000, v4
	v_lshlrev_b32_e32 v60, 16, v5
	v_and_b32_e32 v61, 0xffff0000, v5
	s_waitcnt vmcnt(3)
	v_lshlrev_b32_e32 v20, 16, v180
	s_waitcnt vmcnt(2)
	v_lshlrev_b32_e32 v78, 16, v184
	s_waitcnt vmcnt(1)
	v_lshlrev_b32_e32 v70, 16, v188
	s_waitcnt vmcnt(0)
	v_lshlrev_b32_e32 v62, 16, v192
	v_and_b32_e32 v63, 0xffff0000, v192
	v_lshlrev_b32_e32 v64, 16, v193
	v_and_b32_e32 v65, 0xffff0000, v193
	v_lshlrev_b32_e32 v66, 16, v194
	v_and_b32_e32 v67, 0xffff0000, v194
	v_lshlrev_b32_e32 v68, 16, v195
	v_and_b32_e32 v69, 0xffff0000, v195
	v_and_b32_e32 v71, 0xffff0000, v188
	v_lshlrev_b32_e32 v72, 16, v189
	v_and_b32_e32 v73, 0xffff0000, v189
	v_lshlrev_b32_e32 v74, 16, v190
	v_and_b32_e32 v75, 0xffff0000, v190
	v_lshlrev_b32_e32 v76, 16, v191
	v_and_b32_e32 v77, 0xffff0000, v191
	v_and_b32_e32 v79, 0xffff0000, v184
	v_lshlrev_b32_e32 v80, 16, v185
	v_and_b32_e32 v81, 0xffff0000, v185
	v_lshlrev_b32_e32 v16, 16, v186
	v_and_b32_e32 v17, 0xffff0000, v186
	v_lshlrev_b32_e32 v18, 16, v187
	v_and_b32_e32 v19, 0xffff0000, v187
	v_and_b32_e32 v21, 0xffff0000, v180
	v_lshlrev_b32_e32 v22, 16, v181
	v_and_b32_e32 v23, 0xffff0000, v181
	v_lshlrev_b32_e32 v24, 16, v182
	v_and_b32_e32 v25, 0xffff0000, v182
	v_lshlrev_b32_e32 v26, 16, v183
	v_and_b32_e32 v27, 0xffff0000, v183

; #define LAS __attribute__((address_space(3)))
; #define AT_LOADG(kt, R) do { const size_t krow_ = (size_t)(rowbase + (kt) * 64 + kkey); \
;         kr[R] = *(const u32x4*)(Kb + krow_ * KPITCH + kcol + kch * 8); vr[R] = *(const u32x4*)(Kb + krow_ * KPITCH + vcol + kch * 8); \
;         if (MODE == 0 && tid < 256) pr[R] = *(const u32x4*)(KPEb + (size_t)(rowbase + (kt) * 64 + pkey) * 32 + pch * 8); } while (0)
; #define AT_STORE(bf, R) do { *(LAS u32x4*)(lds + ((bf) ? AT_K1 : AT_K0) + kkey * KP + kch * 16) = kr[R]; *(LAS u32x4*)(lds + ((bf) ? AT_V1 : AT_V0) + kkey * VP + kch * 16) = vr[R]; \
;         if (MODE == 0 && tid < 256) *(LAS u32x4*)(lds + ((bf) ? AT_K1 : AT_K0) + pkey * KP + 128 + pch * 16) = pr[R]; } while (0)
; template <int MODE>
; DI void attn_unit(unsigned char* ws, int b, int h, int qb, LAS unsigned char* lds, bool do_store = true) {
;     ...
;         __syncthreads();
;         mysel = *(LAS unsigned*)(lds + AT_SEL + (32 * w + r) * 4);
;     }
;     const int kkey = tid >> 3, kch = tid & 7, pkey = (tid & 255) >> 2, pch = tid & 3;
;     u32x4 kr[2], vr[2], pr[2];
;     pr[0] = (u32x4){0u, 0u, 0u, 0u}; pr[1] = pr[0];
;     ...
;     const int kt_hi = qb * 4 + 3;
;     AT_LOADG(kt_hi, 0); AT_LOADG(kt_hi - 1, 1); AT_STORE(0, 0);
;     __syncthreads();
.LBB0_140:
	s_or_b64 exec, exec, s[38:39]
	s_lshl_b32 s38, s30, 2
	v_or_b32_e32 v3, s53, v28
	s_or_b32 s53, s38, 3
	v_ashrrev_i32_e32 v4, 3, v14
	s_lshl_b32 s38, s53, 6
	s_add_i32 s38, s38, s2
	s_mov_b32 s39, s3
	v_ashrrev_i32_e32 v5, 31, v4
	v_lshl_add_u32 v3, v3, 2, 0
	v_lshl_add_u64 v[6:7], v[4:5], 0, s[38:39]
	v_mov_b64_e32 v[8:9], s[20:21]
	v_add_u32_e32 v3, 0x10000, v3
	v_mad_u64_u32 v[10:11], s[38:39], v6, s88, v[8:9]
	s_waitcnt lgkmcnt(0)
	s_barrier
	ds_read_b32 v123, v3
	v_mad_i32_i24 v11, v7, s88, v11
	s_lshl_b32 s38, s54, 1
	s_mov_b32 s39, s3
	v_lshlrev_b32_e32 v3, 4, v14
	v_lshl_add_u64 v[6:7], v[10:11], 0, s[38:39]
	v_and_b32_e32 v10, 0x70, v3
	v_mov_b32_e32 v11, v1
	v_lshl_add_u64 v[6:7], v[6:7], 0, v[10:11]
	s_or_b32 s44, s15, 0x80
	s_mov_b32 s45, s3
	v_lshl_add_u64 v[160:161], v[4:5], 0, s[2:3]
	v_lshl_add_u64 v[6:7], v[160:161], 0, s[44:45]
	v_mad_u64_u32 v[8:9], s[44:45], v6, s88, v[8:9]
	v_mad_i32_i24 v9, v7, s88, v9
	v_lshl_add_u64 v[6:7], v[8:9], 0, s[38:39]
	v_lshl_add_u64 v[6:7], v[6:7], 0, v[10:11]
	s_movk_i32 s39, 0x90
	v_mul_lo_u32 v3, v4, s39
	v_add_u32_e32 v6, 0, v3
	v_and_b32_e32 v2, 63, v14
	v_mad_u64_u32 v[4:5], s[44:45], v4, 48, v[6:7]
	v_cmp_gt_u32_e64 s[44:45], 32, v2
	v_mov_b32_e32 v3, 0x7149
	s_or_b32 s54, s52, 31
	v_cndmask_b32_e64 v3, 0, v3, s[44:45]
	v_add_u32_e32 v164, v4, v10
	v_and_b32_e32 v114, 0xffff, v3
	v_lshrrev_b32_e32 v3, 2, v14
	v_and_b32_e32 v4, 16, v14
	v_lshlrev_b32_e32 v165, 2, v29
	s_add_u32 s38, s20, s38
	v_cndmask_b32_e64 v2, 0, v213, s[44:45]
	v_and_or_b32 v3, v3, 3, v165
	v_and_or_b32 v4, v30, 12, v4
	s_movk_i32 s2, 0xc0
	v_mad_u32_u24 v168, v28, s39, 0
	s_addc_u32 s39, s21, 0
	v_mov_b32_e32 v16, v1
	v_mov_b32_e32 v17, v1
	v_add_u32_e32 v159, v6, v10
	v_lshlrev_b32_e32 v166, 1, v4
	v_mad_u32_u24 v167, v3, s2, 0
	v_perm_b32 v116, 0, v2, v214
	s_pack_ll_b32_b16 s2, 0, 0
	v_lshl_add_u64 v[162:163], s[38:39], 0, v[10:11]
	v_mov_b32_e32 v2, v1
	v_mov_b32_e32 v3, v1
	v_mov_b32_e32 v4, v1
	v_mov_b32_e32 v5, v1
	v_mov_b32_e32 v6, v1
	v_mov_b32_e32 v7, v1
	v_mov_b32_e32 v8, v1
	v_mov_b32_e32 v9, v1
	v_mov_b32_e32 v10, v1
	v_mov_b32_e32 v12, v1
	v_mov_b32_e32 v13, v1
	v_mov_b32_e32 v14, v1
	v_mov_b32_e32 v15, v1
	v_mov_b64_e32 v[32:33], v[16:17]
	v_mov_b64_e32 v[48:49], v[16:17]
	v_mov_b32_e32 v117, s2
	v_mov_b32_e32 v118, s2
	v_mov_b32_e32 v119, s2
	v_mov_b32_e32 v120, v1
	v_mov_b32_e32 v115, v1
	v_mov_b32_e32 v122, v1
	v_mov_b32_e32 v121, v1
	s_mov_b64 s[46:47], -1
	v_mov_b32_e32 v169, 0
	v_mov_b64_e32 v[30:31], v[14:15]
	v_mov_b64_e32 v[28:29], v[12:13]
	v_mov_b64_e32 v[26:27], v[10:11]
	v_mov_b64_e32 v[24:25], v[8:9]
	v_mov_b64_e32 v[22:23], v[6:7]
	v_mov_b64_e32 v[20:21], v[4:5]
	v_mov_b64_e32 v[18:19], v[2:3]
	v_mov_b64_e32 v[46:47], v[14:15]
	v_mov_b64_e32 v[44:45], v[12:13]
	v_mov_b64_e32 v[42:43], v[10:11]
	v_mov_b64_e32 v[40:41], v[8:9]
	v_mov_b64_e32 v[38:39], v[6:7]
	v_mov_b64_e32 v[36:37], v[4:5]
	v_mov_b64_e32 v[34:35], v[2:3]
	s_waitcnt vmcnt(0)
	v_mov_b64_e32 v[98:99], v[124:125]
	v_mov_b64_e32 v[100:101], v[126:127]
	v_mov_b64_e32 v[102:103], v[128:129]
	v_mov_b64_e32 v[104:105], v[130:131]
	v_mov_b64_e32 v[106:107], v[132:133]
	v_mov_b64_e32 v[108:109], v[134:135]
	v_mov_b64_e32 v[110:111], v[136:137]
	v_mov_b64_e32 v[112:113], v[138:139]
	s_waitcnt vmcnt(3)
	ds_write_b128 v159, v[98:101]
	s_waitcnt vmcnt(2)
	ds_write_b128 v164, v[102:105] offset:32768
	s_waitcnt lgkmcnt(0)
	s_barrier
